# RS_PUT pair-lane exchange via DPP quad_perm instead of ds_bpermute (G3 and G1), on top of the G3 row-scale read batch
# baseline (speedup 1.0000x reference)
.LBB0_157:
	s_lshl_b32 s38, s79, 10
	s_and_b32 s38, s38, 0x400
	v_add_u32_e32 v161, s38, v158
	ds_read_b32 v244, v161
	ds_read_b32 v245, v161 offset:64
	ds_read_b32 v246, v161 offset:128
	ds_read_b32 v247, v161 offset:192
	ds_read_b32 v248, v161 offset:512
	ds_read_b32 v249, v161 offset:576
	ds_read_b32 v250, v161 offset:640
	ds_read_b32 v251, v161 offset:704
	v_lshl_add_u32 v154, s78, 8, v156
	s_lshl_b32 s38, s77, 8
	v_ashrrev_i32_e32 v155, 31, v154
	s_ashr_i32 s39, s38, 31
	v_lshlrev_b64 v[164:165], 13, v[154:155]
	v_lshl_add_u64 v[164:165], s[30:31], 0, v[164:165]
	s_lshl_b64 s[38:39], s[38:39], 1
	v_lshl_add_u64 v[164:165], v[164:165], 0, s[38:39]
	s_waitcnt lgkmcnt(0)
	v_mov_b32_e32 v162, v244
	v_pk_mul_f32 v[136:137], v[136:137], v[162:163] op_sel_hi:[1,0]
	v_pk_mul_f32 v[134:135], v[134:135], v[162:163] op_sel_hi:[1,0]
	v_pk_mul_f32 v[132:133], v[132:133], v[162:163] op_sel_hi:[1,0]
	v_pk_mul_f32 v[130:131], v[130:131], v[162:163] op_sel_hi:[1,0]
	v_lshl_add_u64 v[164:165], v[164:165], 0, s[50:51]
	v_max_f32_e32 v137, 0, v137
	v_max_f32_e32 v136, 0, v136
	v_max_f32_e32 v135, 0, v135
	v_max_f32_e32 v134, 0, v134
	v_max_f32_e32 v133, 0, v133
	v_max_f32_e32 v132, 0, v132
	v_max_f32_e32 v131, 0, v131
	v_max_f32_e32 v130, 0, v130
	v_pk_mul_f32 v[124:125], v[124:125], v[162:163] op_sel_hi:[1,0]
	v_pk_mul_f32 v[122:123], v[122:123], v[162:163] op_sel_hi:[1,0]
	v_lshl_add_u64 v[164:165], v[164:165], 0, v[152:153]
	v_pk_mul_f32 v[136:137], v[136:137], v[136:137]
	v_pk_mul_f32 v[134:135], v[134:135], v[134:135]
	v_pk_mul_f32 v[166:167], v[132:133], v[132:133]
	v_pk_mul_f32 v[132:133], v[130:131], v[130:131]
	v_cvt_pk_bf16_f32 v130, v134, v135
	v_cvt_pk_bf16_f32 v131, v136, v137
	v_pk_mul_f32 v[128:129], v[128:129], v[162:163] op_sel_hi:[1,0]
	v_pk_mul_f32 v[126:127], v[126:127], v[162:163] op_sel_hi:[1,0]
	v_max_f32_e32 v125, 0, v125
	v_max_f32_e32 v124, 0, v124
	v_max_f32_e32 v123, 0, v123
	v_max_f32_e32 v122, 0, v122
	v_cvt_pk_bf16_f32 v132, v132, v133
	v_cvt_pk_bf16_f32 v133, v166, v167
	global_store_dwordx4 v[164:165], v[130:133], off
	v_max_f32_e32 v129, 0, v129
	v_max_f32_e32 v128, 0, v128
	v_max_f32_e32 v127, 0, v127
	v_max_f32_e32 v126, 0, v126
	v_pk_mul_f32 v[130:131], v[124:125], v[124:125]
	v_pk_mul_f32 v[124:125], v[122:123], v[122:123]
	v_pk_mul_f32 v[128:129], v[128:129], v[128:129]
	v_pk_mul_f32 v[126:127], v[126:127], v[126:127]
	s_and_b64 vcc, exec, s[40:41]
	v_cvt_pk_bf16_f32 v122, v126, v127
	v_cvt_pk_bf16_f32 v123, v128, v129
	v_cvt_pk_bf16_f32 v124, v124, v125
	v_cvt_pk_bf16_f32 v125, v130, v131
	global_store_dwordx4 v[164:165], v[122:125], off offset:256
	s_nop 2
	v_mov_b32_e32 v124, v245
	s_waitcnt lgkmcnt(0)
	v_pk_mul_f32 v[120:121], v[120:121], v[124:125] op_sel_hi:[1,0]
	v_or_b32_e32 v122, 16, v154
	v_ashrrev_i32_e32 v123, 31, v122
	v_lshlrev_b64 v[122:123], 13, v[122:123]
	v_lshl_add_u64 v[122:123], s[30:31], 0, v[122:123]
	v_lshl_add_u64 v[122:123], v[122:123], 0, s[38:39]
	v_pk_mul_f32 v[118:119], v[118:119], v[124:125] op_sel_hi:[1,0]
	v_pk_mul_f32 v[116:117], v[116:117], v[124:125] op_sel_hi:[1,0]
	v_pk_mul_f32 v[114:115], v[114:115], v[124:125] op_sel_hi:[1,0]
	v_lshl_add_u64 v[122:123], v[122:123], 0, s[50:51]
	v_max_f32_e32 v121, 0, v121
	v_max_f32_e32 v120, 0, v120
	v_max_f32_e32 v119, 0, v119
	v_max_f32_e32 v118, 0, v118
	v_max_f32_e32 v117, 0, v117
	v_max_f32_e32 v116, 0, v116
	v_max_f32_e32 v115, 0, v115
	v_max_f32_e32 v114, 0, v114
	v_pk_mul_f32 v[108:109], v[108:109], v[124:125] op_sel_hi:[1,0]
	v_pk_mul_f32 v[106:107], v[106:107], v[124:125] op_sel_hi:[1,0]
	v_lshl_add_u64 v[122:123], v[122:123], 0, v[152:153]
	v_pk_mul_f32 v[120:121], v[120:121], v[120:121]
	v_pk_mul_f32 v[118:119], v[118:119], v[118:119]
	v_pk_mul_f32 v[126:127], v[116:117], v[116:117]
	v_pk_mul_f32 v[116:117], v[114:115], v[114:115]
	v_cvt_pk_bf16_f32 v114, v118, v119
	v_cvt_pk_bf16_f32 v115, v120, v121
	v_pk_mul_f32 v[112:113], v[112:113], v[124:125] op_sel_hi:[1,0]
	v_pk_mul_f32 v[110:111], v[110:111], v[124:125] op_sel_hi:[1,0]
	v_max_f32_e32 v109, 0, v109
	v_max_f32_e32 v108, 0, v108
	v_max_f32_e32 v107, 0, v107
	v_max_f32_e32 v106, 0, v106
	v_cvt_pk_bf16_f32 v116, v116, v117
	v_cvt_pk_bf16_f32 v117, v126, v127
	global_store_dwordx4 v[122:123], v[114:117], off
	v_max_f32_e32 v113, 0, v113
	v_max_f32_e32 v112, 0, v112
	v_max_f32_e32 v111, 0, v111
	v_max_f32_e32 v110, 0, v110
	v_pk_mul_f32 v[114:115], v[108:109], v[108:109]
	v_pk_mul_f32 v[108:109], v[106:107], v[106:107]
	v_pk_mul_f32 v[112:113], v[112:113], v[112:113]
	v_pk_mul_f32 v[110:111], v[110:111], v[110:111]
	s_nop 0
	v_cvt_pk_bf16_f32 v106, v110, v111
	v_cvt_pk_bf16_f32 v107, v112, v113
	v_cvt_pk_bf16_f32 v108, v108, v109
	v_cvt_pk_bf16_f32 v109, v114, v115
	global_store_dwordx4 v[122:123], v[106:109], off offset:256
	s_nop 2
	v_mov_b32_e32 v108, v246
	s_waitcnt lgkmcnt(0)
	v_pk_mul_f32 v[104:105], v[104:105], v[108:109] op_sel_hi:[1,0]
	v_or_b32_e32 v106, 32, v154
	v_ashrrev_i32_e32 v107, 31, v106
	v_lshlrev_b64 v[106:107], 13, v[106:107]
	v_lshl_add_u64 v[106:107], s[30:31], 0, v[106:107]
	v_lshl_add_u64 v[106:107], v[106:107], 0, s[38:39]
	v_pk_mul_f32 v[102:103], v[102:103], v[108:109] op_sel_hi:[1,0]
	v_pk_mul_f32 v[100:101], v[100:101], v[108:109] op_sel_hi:[1,0]
	v_pk_mul_f32 v[98:99], v[98:99], v[108:109] op_sel_hi:[1,0]
	v_lshl_add_u64 v[106:107], v[106:107], 0, s[50:51]
	v_max_f32_e32 v105, 0, v105
	v_max_f32_e32 v104, 0, v104
	v_max_f32_e32 v103, 0, v103
	v_max_f32_e32 v102, 0, v102
	v_max_f32_e32 v101, 0, v101
	v_max_f32_e32 v100, 0, v100
	v_max_f32_e32 v99, 0, v99
	v_max_f32_e32 v98, 0, v98
	v_pk_mul_f32 v[92:93], v[92:93], v[108:109] op_sel_hi:[1,0]
	v_pk_mul_f32 v[90:91], v[90:91], v[108:109] op_sel_hi:[1,0]
	v_lshl_add_u64 v[106:107], v[106:107], 0, v[152:153]
	v_pk_mul_f32 v[104:105], v[104:105], v[104:105]
	v_pk_mul_f32 v[102:103], v[102:103], v[102:103]
	v_pk_mul_f32 v[110:111], v[100:101], v[100:101]
	v_pk_mul_f32 v[100:101], v[98:99], v[98:99]
	v_cvt_pk_bf16_f32 v98, v102, v103
	v_cvt_pk_bf16_f32 v99, v104, v105
	v_pk_mul_f32 v[96:97], v[96:97], v[108:109] op_sel_hi:[1,0]
	v_pk_mul_f32 v[94:95], v[94:95], v[108:109] op_sel_hi:[1,0]
	v_max_f32_e32 v93, 0, v93
	v_max_f32_e32 v92, 0, v92
	v_max_f32_e32 v91, 0, v91
	v_max_f32_e32 v90, 0, v90
	v_cvt_pk_bf16_f32 v100, v100, v101
	v_cvt_pk_bf16_f32 v101, v110, v111
	global_store_dwordx4 v[106:107], v[98:101], off
	v_max_f32_e32 v97, 0, v97
	v_max_f32_e32 v96, 0, v96
	v_max_f32_e32 v95, 0, v95
	v_max_f32_e32 v94, 0, v94
	v_pk_mul_f32 v[98:99], v[92:93], v[92:93]
	v_pk_mul_f32 v[92:93], v[90:91], v[90:91]
	v_pk_mul_f32 v[96:97], v[96:97], v[96:97]
	v_pk_mul_f32 v[94:95], v[94:95], v[94:95]
	s_nop 0
	v_cvt_pk_bf16_f32 v90, v94, v95
	v_cvt_pk_bf16_f32 v91, v96, v97
	v_cvt_pk_bf16_f32 v92, v92, v93
	v_cvt_pk_bf16_f32 v93, v98, v99
	global_store_dwordx4 v[106:107], v[90:93], off offset:256
	s_nop 2
	v_mov_b32_e32 v92, v247
	s_waitcnt lgkmcnt(0)
	v_pk_mul_f32 v[88:89], v[88:89], v[92:93] op_sel_hi:[1,0]
	v_or_b32_e32 v90, 48, v154
	v_ashrrev_i32_e32 v91, 31, v90
	v_lshlrev_b64 v[90:91], 13, v[90:91]
	v_lshl_add_u64 v[90:91], s[30:31], 0, v[90:91]
	v_lshl_add_u64 v[90:91], v[90:91], 0, s[38:39]
	v_pk_mul_f32 v[86:87], v[86:87], v[92:93] op_sel_hi:[1,0]
	v_pk_mul_f32 v[84:85], v[84:85], v[92:93] op_sel_hi:[1,0]
	v_pk_mul_f32 v[82:83], v[82:83], v[92:93] op_sel_hi:[1,0]
	v_lshl_add_u64 v[90:91], v[90:91], 0, s[50:51]
	v_max_f32_e32 v89, 0, v89
	v_max_f32_e32 v88, 0, v88
	v_max_f32_e32 v87, 0, v87
	v_max_f32_e32 v86, 0, v86
	v_max_f32_e32 v85, 0, v85
	v_max_f32_e32 v84, 0, v84
	v_max_f32_e32 v83, 0, v83
	v_max_f32_e32 v82, 0, v82
	v_pk_mul_f32 v[76:77], v[76:77], v[92:93] op_sel_hi:[1,0]
	v_pk_mul_f32 v[74:75], v[74:75], v[92:93] op_sel_hi:[1,0]
	v_lshl_add_u64 v[90:91], v[90:91], 0, v[152:153]
	v_pk_mul_f32 v[88:89], v[88:89], v[88:89]
	v_pk_mul_f32 v[86:87], v[86:87], v[86:87]
	v_pk_mul_f32 v[94:95], v[84:85], v[84:85]
	v_pk_mul_f32 v[84:85], v[82:83], v[82:83]
	v_cvt_pk_bf16_f32 v82, v86, v87
	v_cvt_pk_bf16_f32 v83, v88, v89
	v_pk_mul_f32 v[80:81], v[80:81], v[92:93] op_sel_hi:[1,0]
	v_pk_mul_f32 v[78:79], v[78:79], v[92:93] op_sel_hi:[1,0]
	v_max_f32_e32 v77, 0, v77
	v_max_f32_e32 v76, 0, v76
	v_max_f32_e32 v75, 0, v75
	v_max_f32_e32 v74, 0, v74
	v_cvt_pk_bf16_f32 v84, v84, v85
	v_cvt_pk_bf16_f32 v85, v94, v95
	global_store_dwordx4 v[90:91], v[82:85], off
	v_max_f32_e32 v81, 0, v81
	v_max_f32_e32 v80, 0, v80
	v_max_f32_e32 v79, 0, v79
	v_max_f32_e32 v78, 0, v78
	v_pk_mul_f32 v[82:83], v[76:77], v[76:77]
	v_pk_mul_f32 v[76:77], v[74:75], v[74:75]
	v_pk_mul_f32 v[80:81], v[80:81], v[80:81]
	v_pk_mul_f32 v[78:79], v[78:79], v[78:79]
	s_nop 0
	v_cvt_pk_bf16_f32 v74, v78, v79
	v_cvt_pk_bf16_f32 v75, v80, v81
	v_cvt_pk_bf16_f32 v76, v76, v77
	v_cvt_pk_bf16_f32 v77, v82, v83
	global_store_dwordx4 v[90:91], v[74:77], off offset:256
	s_nop 2
	v_mov_b32_e32 v76, v248
	s_waitcnt lgkmcnt(0)
	v_pk_mul_f32 v[72:73], v[72:73], v[76:77] op_sel_hi:[1,0]
	v_add_u32_e32 v74, 0x80, v154
	v_ashrrev_i32_e32 v75, 31, v74
	v_lshlrev_b64 v[74:75], 13, v[74:75]
	v_lshl_add_u64 v[74:75], s[30:31], 0, v[74:75]
	v_lshl_add_u64 v[74:75], v[74:75], 0, s[38:39]
	v_pk_mul_f32 v[70:71], v[70:71], v[76:77] op_sel_hi:[1,0]
	v_pk_mul_f32 v[68:69], v[68:69], v[76:77] op_sel_hi:[1,0]
	v_pk_mul_f32 v[66:67], v[66:67], v[76:77] op_sel_hi:[1,0]
	v_lshl_add_u64 v[74:75], v[74:75], 0, s[50:51]
	v_max_f32_e32 v73, 0, v73
	v_max_f32_e32 v72, 0, v72
	v_max_f32_e32 v71, 0, v71
	v_max_f32_e32 v70, 0, v70
	v_max_f32_e32 v69, 0, v69
	v_max_f32_e32 v68, 0, v68
	v_max_f32_e32 v67, 0, v67
	v_max_f32_e32 v66, 0, v66
	v_pk_mul_f32 v[60:61], v[60:61], v[76:77] op_sel_hi:[1,0]
	v_pk_mul_f32 v[58:59], v[58:59], v[76:77] op_sel_hi:[1,0]
	v_lshl_add_u64 v[74:75], v[74:75], 0, v[152:153]
	v_pk_mul_f32 v[72:73], v[72:73], v[72:73]
	v_pk_mul_f32 v[70:71], v[70:71], v[70:71]
	v_pk_mul_f32 v[78:79], v[68:69], v[68:69]
	v_pk_mul_f32 v[68:69], v[66:67], v[66:67]
	v_cvt_pk_bf16_f32 v66, v70, v71
	v_cvt_pk_bf16_f32 v67, v72, v73
	v_pk_mul_f32 v[64:65], v[64:65], v[76:77] op_sel_hi:[1,0]
	v_pk_mul_f32 v[62:63], v[62:63], v[76:77] op_sel_hi:[1,0]
	v_max_f32_e32 v61, 0, v61
	v_max_f32_e32 v60, 0, v60
	v_max_f32_e32 v59, 0, v59
	v_max_f32_e32 v58, 0, v58
	v_cvt_pk_bf16_f32 v68, v68, v69
	v_cvt_pk_bf16_f32 v69, v78, v79
	global_store_dwordx4 v[74:75], v[66:69], off
	v_max_f32_e32 v65, 0, v65
	v_max_f32_e32 v64, 0, v64
	v_max_f32_e32 v63, 0, v63
	v_max_f32_e32 v62, 0, v62
	v_pk_mul_f32 v[66:67], v[60:61], v[60:61]
	v_pk_mul_f32 v[60:61], v[58:59], v[58:59]
	v_pk_mul_f32 v[64:65], v[64:65], v[64:65]
	v_pk_mul_f32 v[62:63], v[62:63], v[62:63]
	s_nop 0
	v_cvt_pk_bf16_f32 v58, v62, v63
	v_cvt_pk_bf16_f32 v59, v64, v65
	v_cvt_pk_bf16_f32 v60, v60, v61
	v_cvt_pk_bf16_f32 v61, v66, v67
	global_store_dwordx4 v[74:75], v[58:61], off offset:256
	s_nop 2
	v_mov_b32_e32 v60, v249
	s_waitcnt lgkmcnt(0)
	v_pk_mul_f32 v[56:57], v[56:57], v[60:61] op_sel_hi:[1,0]
	v_add_u32_e32 v58, 0x90, v154
	v_ashrrev_i32_e32 v59, 31, v58
	v_lshlrev_b64 v[58:59], 13, v[58:59]
	v_lshl_add_u64 v[58:59], s[30:31], 0, v[58:59]
	v_lshl_add_u64 v[58:59], v[58:59], 0, s[38:39]
	v_pk_mul_f32 v[54:55], v[54:55], v[60:61] op_sel_hi:[1,0]
	v_pk_mul_f32 v[52:53], v[52:53], v[60:61] op_sel_hi:[1,0]
	v_pk_mul_f32 v[50:51], v[50:51], v[60:61] op_sel_hi:[1,0]
	v_lshl_add_u64 v[58:59], v[58:59], 0, s[50:51]
	v_max_f32_e32 v57, 0, v57
	v_max_f32_e32 v56, 0, v56
	v_max_f32_e32 v55, 0, v55
	v_max_f32_e32 v54, 0, v54
	v_max_f32_e32 v53, 0, v53
	v_max_f32_e32 v52, 0, v52
	v_max_f32_e32 v51, 0, v51
	v_max_f32_e32 v50, 0, v50
	v_pk_mul_f32 v[44:45], v[44:45], v[60:61] op_sel_hi:[1,0]
	v_pk_mul_f32 v[42:43], v[42:43], v[60:61] op_sel_hi:[1,0]
	v_lshl_add_u64 v[58:59], v[58:59], 0, v[152:153]
	v_pk_mul_f32 v[56:57], v[56:57], v[56:57]
	v_pk_mul_f32 v[54:55], v[54:55], v[54:55]
	v_pk_mul_f32 v[62:63], v[52:53], v[52:53]
	v_pk_mul_f32 v[52:53], v[50:51], v[50:51]
	v_cvt_pk_bf16_f32 v50, v54, v55
	v_cvt_pk_bf16_f32 v51, v56, v57
	v_pk_mul_f32 v[48:49], v[48:49], v[60:61] op_sel_hi:[1,0]
	v_pk_mul_f32 v[46:47], v[46:47], v[60:61] op_sel_hi:[1,0]
	v_max_f32_e32 v45, 0, v45
	v_max_f32_e32 v44, 0, v44
	v_max_f32_e32 v43, 0, v43
	v_max_f32_e32 v42, 0, v42
	v_cvt_pk_bf16_f32 v52, v52, v53
	v_cvt_pk_bf16_f32 v53, v62, v63
	global_store_dwordx4 v[58:59], v[50:53], off
	v_max_f32_e32 v49, 0, v49
	v_max_f32_e32 v48, 0, v48
	v_max_f32_e32 v47, 0, v47
	v_max_f32_e32 v46, 0, v46
	v_pk_mul_f32 v[50:51], v[44:45], v[44:45]
	v_pk_mul_f32 v[44:45], v[42:43], v[42:43]
	v_pk_mul_f32 v[48:49], v[48:49], v[48:49]
	v_pk_mul_f32 v[46:47], v[46:47], v[46:47]
	s_nop 0
	v_cvt_pk_bf16_f32 v42, v46, v47
	v_cvt_pk_bf16_f32 v43, v48, v49
	v_cvt_pk_bf16_f32 v44, v44, v45
	v_cvt_pk_bf16_f32 v45, v50, v51
	global_store_dwordx4 v[58:59], v[42:45], off offset:256
	s_nop 2
	v_mov_b32_e32 v44, v250
	s_waitcnt lgkmcnt(0)
	v_pk_mul_f32 v[40:41], v[40:41], v[44:45] op_sel_hi:[1,0]
	v_add_u32_e32 v42, 0xa0, v154
	v_ashrrev_i32_e32 v43, 31, v42
	v_lshlrev_b64 v[42:43], 13, v[42:43]
	v_lshl_add_u64 v[42:43], s[30:31], 0, v[42:43]
	v_lshl_add_u64 v[42:43], v[42:43], 0, s[38:39]
	v_pk_mul_f32 v[38:39], v[38:39], v[44:45] op_sel_hi:[1,0]
	v_pk_mul_f32 v[36:37], v[36:37], v[44:45] op_sel_hi:[1,0]
	v_pk_mul_f32 v[34:35], v[34:35], v[44:45] op_sel_hi:[1,0]
	v_lshl_add_u64 v[42:43], v[42:43], 0, s[50:51]
	v_max_f32_e32 v41, 0, v41
	v_max_f32_e32 v40, 0, v40
	v_max_f32_e32 v39, 0, v39
	v_max_f32_e32 v38, 0, v38
	v_max_f32_e32 v37, 0, v37
	v_max_f32_e32 v36, 0, v36
	v_max_f32_e32 v35, 0, v35
	v_max_f32_e32 v34, 0, v34
	v_pk_mul_f32 v[28:29], v[28:29], v[44:45] op_sel_hi:[1,0]
	v_pk_mul_f32 v[26:27], v[26:27], v[44:45] op_sel_hi:[1,0]
	v_lshl_add_u64 v[42:43], v[42:43], 0, v[152:153]
	v_pk_mul_f32 v[40:41], v[40:41], v[40:41]
	v_pk_mul_f32 v[38:39], v[38:39], v[38:39]
	v_pk_mul_f32 v[46:47], v[36:37], v[36:37]
	v_pk_mul_f32 v[36:37], v[34:35], v[34:35]
	v_cvt_pk_bf16_f32 v34, v38, v39
	v_cvt_pk_bf16_f32 v35, v40, v41
	v_pk_mul_f32 v[32:33], v[32:33], v[44:45] op_sel_hi:[1,0]
	v_pk_mul_f32 v[30:31], v[30:31], v[44:45] op_sel_hi:[1,0]
	v_max_f32_e32 v29, 0, v29
	v_max_f32_e32 v28, 0, v28
	v_max_f32_e32 v27, 0, v27
	v_max_f32_e32 v26, 0, v26
	v_cvt_pk_bf16_f32 v36, v36, v37
	v_cvt_pk_bf16_f32 v37, v46, v47
	global_store_dwordx4 v[42:43], v[34:37], off
	v_max_f32_e32 v33, 0, v33
	v_max_f32_e32 v32, 0, v32
	v_max_f32_e32 v31, 0, v31
	v_max_f32_e32 v30, 0, v30
	v_pk_mul_f32 v[34:35], v[28:29], v[28:29]
	v_pk_mul_f32 v[28:29], v[26:27], v[26:27]
	v_pk_mul_f32 v[32:33], v[32:33], v[32:33]
	v_pk_mul_f32 v[30:31], v[30:31], v[30:31]
	s_nop 0
	v_cvt_pk_bf16_f32 v26, v30, v31
	v_cvt_pk_bf16_f32 v27, v32, v33
	v_cvt_pk_bf16_f32 v28, v28, v29
	v_cvt_pk_bf16_f32 v29, v34, v35
	global_store_dwordx4 v[42:43], v[26:29], off offset:256
	s_nop 2
	v_mov_b32_e32 v28, v251
	s_waitcnt lgkmcnt(0)
	v_pk_mul_f32 v[24:25], v[24:25], v[28:29] op_sel_hi:[1,0]
	v_add_u32_e32 v26, 0xb0, v154
	v_ashrrev_i32_e32 v27, 31, v26
	v_lshlrev_b64 v[26:27], 13, v[26:27]
	v_lshl_add_u64 v[26:27], s[30:31], 0, v[26:27]
	v_lshl_add_u64 v[26:27], v[26:27], 0, s[38:39]
	v_pk_mul_f32 v[22:23], v[22:23], v[28:29] op_sel_hi:[1,0]
	v_pk_mul_f32 v[20:21], v[20:21], v[28:29] op_sel_hi:[1,0]
	v_pk_mul_f32 v[18:19], v[18:19], v[28:29] op_sel_hi:[1,0]
	v_lshl_add_u64 v[26:27], v[26:27], 0, s[50:51]
	v_max_f32_e32 v25, 0, v25
	v_max_f32_e32 v24, 0, v24
	v_max_f32_e32 v23, 0, v23
	v_max_f32_e32 v22, 0, v22
	v_max_f32_e32 v21, 0, v21
	v_max_f32_e32 v20, 0, v20
	v_max_f32_e32 v19, 0, v19
	v_max_f32_e32 v18, 0, v18
	v_pk_mul_f32 v[12:13], v[12:13], v[28:29] op_sel_hi:[1,0]
	v_pk_mul_f32 v[10:11], v[10:11], v[28:29] op_sel_hi:[1,0]
	v_lshl_add_u64 v[26:27], v[26:27], 0, v[152:153]
	v_pk_mul_f32 v[24:25], v[24:25], v[24:25]
	v_pk_mul_f32 v[22:23], v[22:23], v[22:23]
	v_pk_mul_f32 v[30:31], v[20:21], v[20:21]
	v_pk_mul_f32 v[20:21], v[18:19], v[18:19]
	v_cvt_pk_bf16_f32 v18, v22, v23
	v_cvt_pk_bf16_f32 v19, v24, v25
	v_pk_mul_f32 v[16:17], v[16:17], v[28:29] op_sel_hi:[1,0]
	v_pk_mul_f32 v[14:15], v[14:15], v[28:29] op_sel_hi:[1,0]
	v_max_f32_e32 v13, 0, v13
	v_max_f32_e32 v12, 0, v12
	v_max_f32_e32 v11, 0, v11
	v_max_f32_e32 v10, 0, v10
	v_cvt_pk_bf16_f32 v20, v20, v21
	v_cvt_pk_bf16_f32 v21, v30, v31
	global_store_dwordx4 v[26:27], v[18:21], off
	v_max_f32_e32 v17, 0, v17
	v_max_f32_e32 v16, 0, v16
	v_max_f32_e32 v15, 0, v15
	v_max_f32_e32 v14, 0, v14
	v_pk_mul_f32 v[18:19], v[12:13], v[12:13]
	v_pk_mul_f32 v[12:13], v[10:11], v[10:11]
	v_pk_mul_f32 v[16:17], v[16:17], v[16:17]
	v_pk_mul_f32 v[14:15], v[14:15], v[14:15]
	s_mov_b64 s[38:39], -1
	v_cvt_pk_bf16_f32 v10, v14, v15
	v_cvt_pk_bf16_f32 v11, v16, v17
	v_cvt_pk_bf16_f32 v12, v12, v13
	v_cvt_pk_bf16_f32 v13, v18, v19
	global_store_dwordx4 v[26:27], v[10:13], off offset:256
	s_cbranch_vccnz .LBB0_144
	s_waitcnt vmcnt(0)
	v_add_f32_e32 v10, v6, v7
	v_add_f32_e32 v11, v8, v9
	v_add_f32_e32 v10, v10, v11
	v_add_f32_e32 v11, v2, v3
	v_add_f32_e32 v12, v4, v5
	v_add_f32_e32 v11, v11, v12
	v_add_f32_e32 v10, v11, v10
	s_nop 1
	v_mov_b32_dpp v11, v10 quad_perm:[1,0,3,2] row_mask:0xf bank_mask:0xf
	s_nop 1
	s_and_saveexec_b64 s[38:39], s[36:37]
	s_cbranch_execz .LBB0_160
	s_waitcnt lgkmcnt(0)
	v_add_f32_e32 v10, v10, v11
	v_fmamk_f32 v10, v10, 0x3a800000, v220
	v_rsq_f32_e32 v10, v10
	s_lshl_b32 s40, s76, 10
	s_and_b32 s40, s40, 0x400
	v_add_u32_e32 v11, s40, v159
	ds_write_b32 v11, v10

.LBB0_677:
	s_ashr_i32 s42, s83, 1
	s_lshl_b32 s43, s83, 8
	s_and_b32 s59, s43, 0x100
	s_ashr_i32 s43, s42, 31
	s_lshl_b64 s[72:73], s[42:43], 9
	s_mov_b32 s43, s51
	s_lshl_b64 s[78:79], s[42:43], 23
	s_cmp_eq_u32 s42, 6
	s_cselect_b32 s43, 0, s59
	s_cselect_b32 s59, 8, 9
	s_cmp_lt_i32 s42, 2
	s_cselect_b32 s73, s73, s79
	s_cselect_b32 s72, s72, s78
	s_cselect_b32 s42, 10, s59
	s_lshl_b64 s[72:73], s[72:73], 1
	s_add_u32 s59, s76, s72
	s_addc_u32 s61, s77, s73
	s_lshl_b32 s72, s82, 10
	s_and_b32 s72, s72, 0x400
	v_add_u32_e32 v170, s72, v176
	ds_read_b32 v172, v170
	s_lshl_b32 s43, s43, 1
	s_add_u32 s43, s59, s43
	s_addc_u32 s59, s61, 0
	s_add_u32 s72, s43, s50
	s_waitcnt lgkmcnt(0)
	v_pk_mul_f32 v[136:137], v[136:137], v[172:173] op_sel_hi:[1,0]
	v_pk_mul_f32 v[134:135], v[134:135], v[172:173] op_sel_hi:[1,0]
	v_pk_mul_f32 v[188:189], v[136:137], v[136:137]
	v_pk_mul_f32 v[190:191], v[134:135], v[134:135]
	v_pk_mul_f32 v[132:133], v[132:133], v[172:173] op_sel_hi:[1,0]
	v_pk_mov_b32 v[192:193], v[190:191], v[188:189] op_sel:[1,0]
	v_mov_b32_e32 v191, v189
	v_pk_mul_f32 v[130:131], v[130:131], v[172:173] op_sel_hi:[1,0]
	v_pk_add_f32 v[188:189], v[192:193], v[190:191]
	v_pk_mul_f32 v[190:191], v[132:133], v[132:133]
	v_pk_mul_f32 v[192:193], v[130:131], v[130:131]
	v_pk_mul_f32 v[128:129], v[128:129], v[172:173] op_sel_hi:[1,0]
	v_pk_mov_b32 v[196:197], v[192:193], v[190:191] op_sel:[1,0]
	v_mov_b32_e32 v193, v191
	v_pk_add_f32 v[190:191], v[196:197], v[192:193]
	v_pk_mul_f32 v[192:193], v[126:127], v[172:173] op_sel_hi:[1,0]
	v_pk_add_f32 v[188:189], v[188:189], v[188:189] op_sel_hi:[0,1]
	v_mul_f32_e32 v126, v192, v192
	v_pk_fma_f32 v[126:127], v[192:193], v[192:193], v[126:127] op_sel_hi:[1,1,0]
	v_pk_add_f32 v[190:191], v[190:191], v[190:191] op_sel_hi:[0,1]
	v_mul_f32_e32 v126, v128, v128
	v_pk_fma_f32 v[196:197], v[128:129], v[128:129], v[126:127] op_sel_hi:[1,1,0]
	v_pk_mul_f32 v[198:199], v[124:125], v[172:173] op_sel_hi:[1,0]
	v_pk_mul_f32 v[172:173], v[122:123], v[172:173] op_sel_hi:[1,0]
	v_mul_f32_e32 v188, v198, v198
	v_mul_f32_e32 v126, v172, v172
	v_mul_f32_e32 v196, v173, v173
	v_mul_f32_e32 v190, v199, v199
	v_pk_add_f32 v[122:123], v[126:127], v[196:197]
	v_pk_add_f32 v[124:125], v[188:189], v[190:191]
	s_addc_u32 s73, s59, 0
	v_pk_add_f32 v[122:123], v[122:123], v[124:125]
	s_lshl_b32 s43, s81, 8
	v_add_f32_e32 v122, v122, v123
	v_mov_b32_e32 v123, v122
	s_nop 1
	v_permlane16_swap_b32 v122, v123
	s_nop 1
	v_add_f32_e32 v122, v122, v123
	v_add_u32_e32 v124, s43, v174
	s_and_b64 vcc, exec, s[38:39]
	s_mov_b64 s[38:39], -1
	v_mov_b32_e32 v123, v122
	s_nop 1
	v_permlane32_swap_b32 v122, v123
	s_nop 1
	v_add_f32_e32 v122, v122, v123
	v_fmamk_f32 v122, v122, 0x3c800000, v220
	v_rsq_f32_e32 v125, v122
	v_lshl_add_u64 v[122:123], v[146:147], 1, s[72:73]
	v_cndmask_b32_e64 v188, 1.0, v125, s[40:41]
	v_ashrrev_i32_e32 v125, 31, v124
	v_lshlrev_b64 v[124:125], s42, v[124:125]
	v_lshl_add_u64 v[190:191], v[124:125], 1, v[122:123]
	v_pk_mul_f32 v[124:125], v[134:135], v[188:189] op_sel_hi:[1,0]
	v_pk_mul_f32 v[126:127], v[136:137], v[188:189] op_sel_hi:[1,0]
	v_pk_mul_f32 v[124:125], v[156:157], v[124:125]
	v_pk_mul_f32 v[126:127], v[158:159], v[126:127]
	v_pk_mul_f32 v[130:131], v[130:131], v[188:189] op_sel_hi:[1,0]
	v_pk_mul_f32 v[132:133], v[132:133], v[188:189] op_sel_hi:[1,0]
	v_pk_mul_f32 v[130:131], v[154:155], v[130:131]
	v_pk_mul_f32 v[132:133], v[160:161], v[132:133]
	v_cvt_pk_bf16_f32 v124, v124, v125
	v_cvt_pk_bf16_f32 v125, v126, v127
	v_cvt_pk_bf16_f32 v126, v130, v131
	v_pk_mul_f32 v[130:131], v[198:199], v[188:189] op_sel_hi:[1,0]
	v_cvt_pk_bf16_f32 v127, v132, v133
	global_store_dwordx4 v[190:191], v[124:127], off
	v_pk_mul_f32 v[130:131], v[168:169], v[130:131]
	s_nop 0
	v_pk_mul_f32 v[124:125], v[192:193], v[188:189] op_sel_hi:[1,0]
	v_pk_mul_f32 v[126:127], v[128:129], v[188:189] op_sel_hi:[1,0]
	v_pk_mul_f32 v[124:125], v[164:165], v[124:125]
	v_pk_mul_f32 v[126:127], v[166:167], v[126:127]
	v_pk_mul_f32 v[128:129], v[172:173], v[188:189] op_sel_hi:[1,0]
	v_cvt_pk_bf16_f32 v124, v124, v125
	v_cvt_pk_bf16_f32 v125, v126, v127
	s_nop 0
	v_pk_mul_f32 v[128:129], v[162:163], v[128:129]
	s_nop 0
	v_cvt_pk_bf16_f32 v126, v128, v129
	v_cvt_pk_bf16_f32 v127, v130, v131
	global_store_dwordx4 v[190:191], v[124:127], off offset:64
	ds_read_b32 v124, v170 offset:64
	s_waitcnt lgkmcnt(0)
	v_pk_mul_f32 v[120:121], v[120:121], v[124:125] op_sel_hi:[1,0]
	v_pk_mul_f32 v[118:119], v[118:119], v[124:125] op_sel_hi:[1,0]
	v_pk_mul_f32 v[126:127], v[120:121], v[120:121]
	v_pk_mul_f32 v[128:129], v[118:119], v[118:119]
	v_pk_mul_f32 v[116:117], v[116:117], v[124:125] op_sel_hi:[1,0]
	v_pk_mov_b32 v[130:131], v[128:129], v[126:127] op_sel:[1,0]
	v_mov_b32_e32 v129, v127
	v_pk_add_f32 v[126:127], v[130:131], v[128:129]
	v_pk_mul_f32 v[114:115], v[114:115], v[124:125] op_sel_hi:[1,0]
	v_pk_add_f32 v[126:127], v[126:127], v[126:127] op_sel_hi:[0,1]
	v_pk_mul_f32 v[128:129], v[116:117], v[116:117]
	v_pk_mul_f32 v[130:131], v[114:115], v[114:115]
	v_pk_mul_f32 v[110:111], v[110:111], v[124:125] op_sel_hi:[1,0]
	v_pk_mov_b32 v[132:133], v[130:131], v[128:129] op_sel:[1,0]
	v_mov_b32_e32 v131, v129
	v_pk_mul_f32 v[112:113], v[112:113], v[124:125] op_sel_hi:[1,0]
	v_mul_f32_e32 v126, v110, v110
	v_pk_add_f32 v[128:129], v[132:133], v[130:131]
	v_pk_fma_f32 v[130:131], v[110:111], v[110:111], v[126:127] op_sel_hi:[1,1,0]
	v_mul_f32_e32 v126, v112, v112
	v_pk_add_f32 v[128:129], v[128:129], v[128:129] op_sel_hi:[0,1]
	v_pk_fma_f32 v[132:133], v[112:113], v[112:113], v[126:127] op_sel_hi:[1,1,0]
	v_pk_mul_f32 v[134:135], v[108:109], v[124:125] op_sel_hi:[1,0]
	v_pk_mul_f32 v[124:125], v[106:107], v[124:125] op_sel_hi:[1,0]
	v_mul_f32_e32 v126, v134, v134
	v_mul_f32_e32 v130, v124, v124
	v_mul_f32_e32 v132, v125, v125
	v_mul_f32_e32 v128, v135, v135
	v_pk_add_f32 v[106:107], v[130:131], v[132:133]
	v_pk_add_f32 v[108:109], v[126:127], v[128:129]
	s_nop 0
	v_pk_add_f32 v[106:107], v[106:107], v[108:109]
	s_nop 0
	v_add_f32_e32 v106, v106, v107
	v_mov_b32_e32 v107, v106
	s_nop 1
	v_permlane16_swap_b32 v106, v107
	s_nop 1
	v_add_f32_e32 v106, v106, v107
	v_mov_b32_e32 v107, v106
	s_nop 1
	v_permlane32_swap_b32 v106, v107
	s_nop 1
	v_add_f32_e32 v106, v106, v107
	v_fmamk_f32 v106, v106, 0x3c800000, v220
	v_rsq_f32_e32 v107, v106
	v_add_u32_e32 v106, s43, v180
	v_cndmask_b32_e64 v126, 1.0, v107, s[40:41]
	v_ashrrev_i32_e32 v107, 31, v106
	v_lshlrev_b64 v[106:107], s42, v[106:107]
	v_lshl_add_u64 v[128:129], v[106:107], 1, v[122:123]
	v_pk_mul_f32 v[106:107], v[118:119], v[126:127] op_sel_hi:[1,0]
	v_pk_mul_f32 v[108:109], v[120:121], v[126:127] op_sel_hi:[1,0]
	v_pk_mul_f32 v[106:107], v[156:157], v[106:107]
	v_pk_mul_f32 v[108:109], v[158:159], v[108:109]
	v_pk_mul_f32 v[114:115], v[114:115], v[126:127] op_sel_hi:[1,0]
	v_pk_mul_f32 v[116:117], v[116:117], v[126:127] op_sel_hi:[1,0]
	v_pk_mul_f32 v[114:115], v[154:155], v[114:115]
	v_pk_mul_f32 v[116:117], v[160:161], v[116:117]
	v_cvt_pk_bf16_f32 v106, v106, v107
	v_cvt_pk_bf16_f32 v107, v108, v109
	v_cvt_pk_bf16_f32 v108, v114, v115
	s_nop 0
	v_cvt_pk_bf16_f32 v109, v116, v117
	global_store_dwordx4 v[128:129], v[106:109], off
	s_nop 1
	v_pk_mul_f32 v[106:107], v[110:111], v[126:127] op_sel_hi:[1,0]
	v_pk_mul_f32 v[108:109], v[112:113], v[126:127] op_sel_hi:[1,0]
	v_pk_mul_f32 v[106:107], v[164:165], v[106:107]
	v_pk_mul_f32 v[108:109], v[166:167], v[108:109]
	v_pk_mul_f32 v[110:111], v[124:125], v[126:127] op_sel_hi:[1,0]
	v_pk_mul_f32 v[112:113], v[134:135], v[126:127] op_sel_hi:[1,0]
	v_pk_mul_f32 v[110:111], v[162:163], v[110:111]
	v_pk_mul_f32 v[112:113], v[168:169], v[112:113]
	v_cvt_pk_bf16_f32 v106, v106, v107
	v_cvt_pk_bf16_f32 v107, v108, v109
	v_cvt_pk_bf16_f32 v108, v110, v111
	s_nop 0
	v_cvt_pk_bf16_f32 v109, v112, v113
	global_store_dwordx4 v[128:129], v[106:109], off offset:64
	ds_read_b32 v106, v170 offset:128
	s_waitcnt lgkmcnt(0)
	v_pk_mul_f32 v[104:105], v[104:105], v[106:107] op_sel_hi:[1,0]
	v_pk_mul_f32 v[102:103], v[102:103], v[106:107] op_sel_hi:[1,0]
	v_pk_mul_f32 v[108:109], v[104:105], v[104:105]
	v_pk_mul_f32 v[110:111], v[102:103], v[102:103]
	v_pk_mul_f32 v[100:101], v[100:101], v[106:107] op_sel_hi:[1,0]
	v_pk_mov_b32 v[112:113], v[110:111], v[108:109] op_sel:[1,0]
	v_mov_b32_e32 v111, v109
	v_pk_add_f32 v[108:109], v[112:113], v[110:111]
	v_pk_mul_f32 v[98:99], v[98:99], v[106:107] op_sel_hi:[1,0]
	v_pk_add_f32 v[108:109], v[108:109], v[108:109] op_sel_hi:[0,1]
	v_pk_mul_f32 v[110:111], v[100:101], v[100:101]
	v_pk_mul_f32 v[112:113], v[98:99], v[98:99]
	v_pk_mul_f32 v[94:95], v[94:95], v[106:107] op_sel_hi:[1,0]
	v_pk_mov_b32 v[114:115], v[112:113], v[110:111] op_sel:[1,0]
	v_mov_b32_e32 v113, v111
	v_pk_mul_f32 v[96:97], v[96:97], v[106:107] op_sel_hi:[1,0]
	v_mul_f32_e32 v108, v94, v94
	v_pk_add_f32 v[110:111], v[114:115], v[112:113]
	v_pk_fma_f32 v[112:113], v[94:95], v[94:95], v[108:109] op_sel_hi:[1,1,0]
	v_mul_f32_e32 v108, v96, v96
	v_pk_add_f32 v[110:111], v[110:111], v[110:111] op_sel_hi:[0,1]
	v_pk_fma_f32 v[114:115], v[96:97], v[96:97], v[108:109] op_sel_hi:[1,1,0]
	v_pk_mul_f32 v[116:117], v[92:93], v[106:107] op_sel_hi:[1,0]
	v_pk_mul_f32 v[106:107], v[90:91], v[106:107] op_sel_hi:[1,0]
	v_mul_f32_e32 v108, v116, v116
	v_mul_f32_e32 v112, v106, v106
	v_mul_f32_e32 v114, v107, v107
	v_mul_f32_e32 v110, v117, v117
	v_pk_add_f32 v[90:91], v[112:113], v[114:115]
	v_pk_add_f32 v[92:93], v[108:109], v[110:111]
	s_nop 0
	v_pk_add_f32 v[90:91], v[90:91], v[92:93]
	s_nop 0
	v_add_f32_e32 v90, v90, v91
	v_mov_b32_e32 v91, v90
	s_nop 1
	v_permlane16_swap_b32 v90, v91
	s_nop 1
	v_add_f32_e32 v90, v90, v91
	v_mov_b32_e32 v91, v90
	s_nop 1
	v_permlane32_swap_b32 v90, v91
	s_nop 1
	v_add_f32_e32 v90, v90, v91
	v_fmamk_f32 v90, v90, 0x3c800000, v220
	v_rsq_f32_e32 v91, v90
	v_add_u32_e32 v90, s43, v181
	v_cndmask_b32_e64 v108, 1.0, v91, s[40:41]
	v_ashrrev_i32_e32 v91, 31, v90
	v_lshlrev_b64 v[90:91], s42, v[90:91]
	v_lshl_add_u64 v[110:111], v[90:91], 1, v[122:123]
	v_pk_mul_f32 v[90:91], v[102:103], v[108:109] op_sel_hi:[1,0]
	v_pk_mul_f32 v[92:93], v[104:105], v[108:109] op_sel_hi:[1,0]
	v_pk_mul_f32 v[90:91], v[156:157], v[90:91]
	v_pk_mul_f32 v[92:93], v[158:159], v[92:93]
	v_pk_mul_f32 v[98:99], v[98:99], v[108:109] op_sel_hi:[1,0]
	v_pk_mul_f32 v[100:101], v[100:101], v[108:109] op_sel_hi:[1,0]
	v_pk_mul_f32 v[98:99], v[154:155], v[98:99]
	v_pk_mul_f32 v[100:101], v[160:161], v[100:101]
	v_cvt_pk_bf16_f32 v90, v90, v91
	v_cvt_pk_bf16_f32 v91, v92, v93
	v_cvt_pk_bf16_f32 v92, v98, v99
	s_nop 0
	v_cvt_pk_bf16_f32 v93, v100, v101
	global_store_dwordx4 v[110:111], v[90:93], off
	s_nop 1
	v_pk_mul_f32 v[90:91], v[94:95], v[108:109] op_sel_hi:[1,0]
	v_pk_mul_f32 v[92:93], v[96:97], v[108:109] op_sel_hi:[1,0]
	v_pk_mul_f32 v[90:91], v[164:165], v[90:91]
	v_pk_mul_f32 v[92:93], v[166:167], v[92:93]
	v_pk_mul_f32 v[94:95], v[106:107], v[108:109] op_sel_hi:[1,0]
	v_pk_mul_f32 v[96:97], v[116:117], v[108:109] op_sel_hi:[1,0]
	v_pk_mul_f32 v[94:95], v[162:163], v[94:95]
	v_pk_mul_f32 v[96:97], v[168:169], v[96:97]
	v_cvt_pk_bf16_f32 v90, v90, v91
	v_cvt_pk_bf16_f32 v91, v92, v93
	v_cvt_pk_bf16_f32 v92, v94, v95
	s_nop 0
	v_cvt_pk_bf16_f32 v93, v96, v97
	global_store_dwordx4 v[110:111], v[90:93], off offset:64
	ds_read_b32 v90, v170 offset:192
	s_waitcnt lgkmcnt(0)
	v_pk_mul_f32 v[88:89], v[88:89], v[90:91] op_sel_hi:[1,0]
	v_pk_mul_f32 v[86:87], v[86:87], v[90:91] op_sel_hi:[1,0]
	v_pk_mul_f32 v[92:93], v[88:89], v[88:89]
	v_pk_mul_f32 v[94:95], v[86:87], v[86:87]
	v_pk_mul_f32 v[84:85], v[84:85], v[90:91] op_sel_hi:[1,0]
	v_pk_mov_b32 v[96:97], v[94:95], v[92:93] op_sel:[1,0]
	v_mov_b32_e32 v95, v93
	v_pk_add_f32 v[92:93], v[96:97], v[94:95]
	v_pk_mul_f32 v[82:83], v[82:83], v[90:91] op_sel_hi:[1,0]
	v_pk_add_f32 v[92:93], v[92:93], v[92:93] op_sel_hi:[0,1]
	v_pk_mul_f32 v[94:95], v[84:85], v[84:85]
	v_pk_mul_f32 v[96:97], v[82:83], v[82:83]
	v_pk_mul_f32 v[78:79], v[78:79], v[90:91] op_sel_hi:[1,0]
	v_pk_mov_b32 v[98:99], v[96:97], v[94:95] op_sel:[1,0]
	v_mov_b32_e32 v97, v95
	v_pk_mul_f32 v[80:81], v[80:81], v[90:91] op_sel_hi:[1,0]
	v_mul_f32_e32 v92, v78, v78
	v_pk_add_f32 v[94:95], v[98:99], v[96:97]
	v_pk_fma_f32 v[96:97], v[78:79], v[78:79], v[92:93] op_sel_hi:[1,1,0]
	v_mul_f32_e32 v92, v80, v80
	v_pk_add_f32 v[94:95], v[94:95], v[94:95] op_sel_hi:[0,1]
	v_pk_fma_f32 v[98:99], v[80:81], v[80:81], v[92:93] op_sel_hi:[1,1,0]
	v_pk_mul_f32 v[100:101], v[76:77], v[90:91] op_sel_hi:[1,0]
	v_pk_mul_f32 v[90:91], v[74:75], v[90:91] op_sel_hi:[1,0]
	v_mul_f32_e32 v92, v100, v100
	v_mul_f32_e32 v96, v90, v90
	v_mul_f32_e32 v98, v91, v91
	v_mul_f32_e32 v94, v101, v101
	v_pk_add_f32 v[74:75], v[96:97], v[98:99]
	v_pk_add_f32 v[76:77], v[92:93], v[94:95]
	s_nop 0
	v_pk_add_f32 v[74:75], v[74:75], v[76:77]
	s_nop 0
	v_add_f32_e32 v74, v74, v75
	v_mov_b32_e32 v75, v74
	s_nop 1
	v_permlane16_swap_b32 v74, v75
	s_nop 1
	v_add_f32_e32 v74, v74, v75
	v_mov_b32_e32 v75, v74
	s_nop 1
	v_permlane32_swap_b32 v74, v75
	s_nop 1
	v_add_f32_e32 v74, v74, v75
	v_fmamk_f32 v74, v74, 0x3c800000, v220
	v_rsq_f32_e32 v75, v74
	v_add_u32_e32 v74, s43, v182
	v_cndmask_b32_e64 v92, 1.0, v75, s[40:41]
	v_ashrrev_i32_e32 v75, 31, v74
	v_lshlrev_b64 v[74:75], s42, v[74:75]
	v_lshl_add_u64 v[94:95], v[74:75], 1, v[122:123]
	v_pk_mul_f32 v[74:75], v[86:87], v[92:93] op_sel_hi:[1,0]
	v_pk_mul_f32 v[76:77], v[88:89], v[92:93] op_sel_hi:[1,0]
	v_pk_mul_f32 v[74:75], v[156:157], v[74:75]
	v_pk_mul_f32 v[76:77], v[158:159], v[76:77]
	v_pk_mul_f32 v[82:83], v[82:83], v[92:93] op_sel_hi:[1,0]
	v_pk_mul_f32 v[84:85], v[84:85], v[92:93] op_sel_hi:[1,0]
	v_pk_mul_f32 v[82:83], v[154:155], v[82:83]
	v_pk_mul_f32 v[84:85], v[160:161], v[84:85]
	v_cvt_pk_bf16_f32 v74, v74, v75
	v_cvt_pk_bf16_f32 v75, v76, v77
	v_cvt_pk_bf16_f32 v76, v82, v83
	s_nop 0
	v_cvt_pk_bf16_f32 v77, v84, v85
	global_store_dwordx4 v[94:95], v[74:77], off
	s_nop 1
	v_pk_mul_f32 v[74:75], v[78:79], v[92:93] op_sel_hi:[1,0]
	v_pk_mul_f32 v[76:77], v[80:81], v[92:93] op_sel_hi:[1,0]
	v_pk_mul_f32 v[74:75], v[164:165], v[74:75]
	v_pk_mul_f32 v[76:77], v[166:167], v[76:77]
	v_pk_mul_f32 v[78:79], v[90:91], v[92:93] op_sel_hi:[1,0]
	v_pk_mul_f32 v[80:81], v[100:101], v[92:93] op_sel_hi:[1,0]
	v_pk_mul_f32 v[78:79], v[162:163], v[78:79]
	v_pk_mul_f32 v[80:81], v[168:169], v[80:81]
	v_cvt_pk_bf16_f32 v74, v74, v75
	v_cvt_pk_bf16_f32 v75, v76, v77
	v_cvt_pk_bf16_f32 v76, v78, v79
	s_nop 0
	v_cvt_pk_bf16_f32 v77, v80, v81
	global_store_dwordx4 v[94:95], v[74:77], off offset:64
	ds_read_b32 v74, v170 offset:512
	s_waitcnt lgkmcnt(0)
	v_pk_mul_f32 v[72:73], v[72:73], v[74:75] op_sel_hi:[1,0]
	v_pk_mul_f32 v[70:71], v[70:71], v[74:75] op_sel_hi:[1,0]
	v_pk_mul_f32 v[76:77], v[72:73], v[72:73]
	v_pk_mul_f32 v[78:79], v[70:71], v[70:71]
	v_pk_mul_f32 v[68:69], v[68:69], v[74:75] op_sel_hi:[1,0]
	v_pk_mov_b32 v[80:81], v[78:79], v[76:77] op_sel:[1,0]
	v_mov_b32_e32 v79, v77
	v_pk_add_f32 v[76:77], v[80:81], v[78:79]
	v_pk_mul_f32 v[66:67], v[66:67], v[74:75] op_sel_hi:[1,0]
	v_pk_add_f32 v[76:77], v[76:77], v[76:77] op_sel_hi:[0,1]
	v_pk_mul_f32 v[78:79], v[68:69], v[68:69]
	v_pk_mul_f32 v[80:81], v[66:67], v[66:67]
	v_pk_mul_f32 v[62:63], v[62:63], v[74:75] op_sel_hi:[1,0]
	v_pk_mov_b32 v[82:83], v[80:81], v[78:79] op_sel:[1,0]
	v_mov_b32_e32 v81, v79
	v_pk_mul_f32 v[64:65], v[64:65], v[74:75] op_sel_hi:[1,0]
	v_mul_f32_e32 v76, v62, v62
	v_pk_add_f32 v[78:79], v[82:83], v[80:81]
	v_pk_fma_f32 v[80:81], v[62:63], v[62:63], v[76:77] op_sel_hi:[1,1,0]
	v_mul_f32_e32 v76, v64, v64
	v_pk_add_f32 v[78:79], v[78:79], v[78:79] op_sel_hi:[0,1]
	v_pk_fma_f32 v[82:83], v[64:65], v[64:65], v[76:77] op_sel_hi:[1,1,0]
	v_pk_mul_f32 v[84:85], v[60:61], v[74:75] op_sel_hi:[1,0]
	v_pk_mul_f32 v[74:75], v[58:59], v[74:75] op_sel_hi:[1,0]
	v_mul_f32_e32 v76, v84, v84
	v_mul_f32_e32 v80, v74, v74
	v_mul_f32_e32 v82, v75, v75
	v_mul_f32_e32 v78, v85, v85
	v_pk_add_f32 v[58:59], v[80:81], v[82:83]
	v_pk_add_f32 v[60:61], v[76:77], v[78:79]
	s_nop 0
	v_pk_add_f32 v[58:59], v[58:59], v[60:61]
	s_nop 0
	v_add_f32_e32 v58, v58, v59
	v_mov_b32_e32 v59, v58
	s_nop 1
	v_permlane16_swap_b32 v58, v59
	s_nop 1
	v_add_f32_e32 v58, v58, v59
	v_mov_b32_e32 v59, v58
	s_nop 1
	v_permlane32_swap_b32 v58, v59
	s_nop 1
	v_add_f32_e32 v58, v58, v59
	v_fmamk_f32 v58, v58, 0x3c800000, v220
	v_rsq_f32_e32 v59, v58
	v_add_u32_e32 v58, s43, v183
	v_cndmask_b32_e64 v76, 1.0, v59, s[40:41]
	v_ashrrev_i32_e32 v59, 31, v58
	v_lshlrev_b64 v[58:59], s42, v[58:59]
	v_lshl_add_u64 v[78:79], v[58:59], 1, v[122:123]
	v_pk_mul_f32 v[58:59], v[70:71], v[76:77] op_sel_hi:[1,0]
	v_pk_mul_f32 v[60:61], v[72:73], v[76:77] op_sel_hi:[1,0]
	v_pk_mul_f32 v[58:59], v[156:157], v[58:59]
	v_pk_mul_f32 v[60:61], v[158:159], v[60:61]
	v_pk_mul_f32 v[66:67], v[66:67], v[76:77] op_sel_hi:[1,0]
	v_pk_mul_f32 v[68:69], v[68:69], v[76:77] op_sel_hi:[1,0]
	v_pk_mul_f32 v[66:67], v[154:155], v[66:67]
	v_pk_mul_f32 v[68:69], v[160:161], v[68:69]
	v_cvt_pk_bf16_f32 v58, v58, v59
	v_cvt_pk_bf16_f32 v59, v60, v61
	v_cvt_pk_bf16_f32 v60, v66, v67
	s_nop 0
	v_cvt_pk_bf16_f32 v61, v68, v69
	global_store_dwordx4 v[78:79], v[58:61], off
	s_nop 1
	v_pk_mul_f32 v[58:59], v[62:63], v[76:77] op_sel_hi:[1,0]
	v_pk_mul_f32 v[60:61], v[64:65], v[76:77] op_sel_hi:[1,0]
	v_pk_mul_f32 v[58:59], v[164:165], v[58:59]
	v_pk_mul_f32 v[60:61], v[166:167], v[60:61]
	v_pk_mul_f32 v[62:63], v[74:75], v[76:77] op_sel_hi:[1,0]
	v_pk_mul_f32 v[64:65], v[84:85], v[76:77] op_sel_hi:[1,0]
	v_pk_mul_f32 v[62:63], v[162:163], v[62:63]
	v_pk_mul_f32 v[64:65], v[168:169], v[64:65]
	v_cvt_pk_bf16_f32 v58, v58, v59
	v_cvt_pk_bf16_f32 v59, v60, v61
	v_cvt_pk_bf16_f32 v60, v62, v63
	s_nop 0
	v_cvt_pk_bf16_f32 v61, v64, v65
	global_store_dwordx4 v[78:79], v[58:61], off offset:64
	ds_read_b32 v58, v170 offset:576
	s_waitcnt lgkmcnt(0)
	v_pk_mul_f32 v[56:57], v[56:57], v[58:59] op_sel_hi:[1,0]
	v_pk_mul_f32 v[54:55], v[54:55], v[58:59] op_sel_hi:[1,0]
	v_pk_mul_f32 v[60:61], v[56:57], v[56:57]
	v_pk_mul_f32 v[62:63], v[54:55], v[54:55]
	v_pk_mul_f32 v[52:53], v[52:53], v[58:59] op_sel_hi:[1,0]
	v_pk_mov_b32 v[64:65], v[62:63], v[60:61] op_sel:[1,0]
	v_mov_b32_e32 v63, v61
	v_pk_add_f32 v[60:61], v[64:65], v[62:63]
	v_pk_mul_f32 v[50:51], v[50:51], v[58:59] op_sel_hi:[1,0]
	v_pk_add_f32 v[60:61], v[60:61], v[60:61] op_sel_hi:[0,1]
	v_pk_mul_f32 v[62:63], v[52:53], v[52:53]
	v_pk_mul_f32 v[64:65], v[50:51], v[50:51]
	v_pk_mul_f32 v[46:47], v[46:47], v[58:59] op_sel_hi:[1,0]
	v_pk_mov_b32 v[66:67], v[64:65], v[62:63] op_sel:[1,0]
	v_mov_b32_e32 v65, v63
	v_pk_mul_f32 v[48:49], v[48:49], v[58:59] op_sel_hi:[1,0]
	v_mul_f32_e32 v60, v46, v46
	v_pk_add_f32 v[62:63], v[66:67], v[64:65]
	v_pk_fma_f32 v[64:65], v[46:47], v[46:47], v[60:61] op_sel_hi:[1,1,0]
	v_mul_f32_e32 v60, v48, v48
	v_pk_add_f32 v[62:63], v[62:63], v[62:63] op_sel_hi:[0,1]
	v_pk_fma_f32 v[66:67], v[48:49], v[48:49], v[60:61] op_sel_hi:[1,1,0]
	v_pk_mul_f32 v[68:69], v[44:45], v[58:59] op_sel_hi:[1,0]
	v_pk_mul_f32 v[58:59], v[42:43], v[58:59] op_sel_hi:[1,0]
	v_mul_f32_e32 v60, v68, v68
	v_mul_f32_e32 v64, v58, v58
	v_mul_f32_e32 v66, v59, v59
	v_mul_f32_e32 v62, v69, v69
	v_pk_add_f32 v[42:43], v[64:65], v[66:67]
	v_pk_add_f32 v[44:45], v[60:61], v[62:63]
	s_nop 0
	v_pk_add_f32 v[42:43], v[42:43], v[44:45]
	s_nop 0
	v_add_f32_e32 v42, v42, v43
	v_mov_b32_e32 v43, v42
	s_nop 1
	v_permlane16_swap_b32 v42, v43
	s_nop 1
	v_add_f32_e32 v42, v42, v43
	v_mov_b32_e32 v43, v42
	s_nop 1
	v_permlane32_swap_b32 v42, v43
	s_nop 1
	v_add_f32_e32 v42, v42, v43
	v_fmamk_f32 v42, v42, 0x3c800000, v220
	v_rsq_f32_e32 v43, v42
	v_add_u32_e32 v42, s43, v184
	v_cndmask_b32_e64 v60, 1.0, v43, s[40:41]
	v_ashrrev_i32_e32 v43, 31, v42
	v_lshlrev_b64 v[42:43], s42, v[42:43]
	v_lshl_add_u64 v[62:63], v[42:43], 1, v[122:123]
	v_pk_mul_f32 v[42:43], v[54:55], v[60:61] op_sel_hi:[1,0]
	v_pk_mul_f32 v[44:45], v[56:57], v[60:61] op_sel_hi:[1,0]
	v_pk_mul_f32 v[42:43], v[156:157], v[42:43]
	v_pk_mul_f32 v[44:45], v[158:159], v[44:45]
	v_pk_mul_f32 v[50:51], v[50:51], v[60:61] op_sel_hi:[1,0]
	v_pk_mul_f32 v[52:53], v[52:53], v[60:61] op_sel_hi:[1,0]
	v_pk_mul_f32 v[50:51], v[154:155], v[50:51]
	v_pk_mul_f32 v[52:53], v[160:161], v[52:53]
	v_cvt_pk_bf16_f32 v42, v42, v43
	v_cvt_pk_bf16_f32 v43, v44, v45
	v_cvt_pk_bf16_f32 v44, v50, v51
	s_nop 0
	v_cvt_pk_bf16_f32 v45, v52, v53
	global_store_dwordx4 v[62:63], v[42:45], off
	s_nop 1
	v_pk_mul_f32 v[42:43], v[46:47], v[60:61] op_sel_hi:[1,0]
	v_pk_mul_f32 v[44:45], v[48:49], v[60:61] op_sel_hi:[1,0]
	v_pk_mul_f32 v[42:43], v[164:165], v[42:43]
	v_pk_mul_f32 v[44:45], v[166:167], v[44:45]
	v_pk_mul_f32 v[46:47], v[58:59], v[60:61] op_sel_hi:[1,0]
	v_pk_mul_f32 v[48:49], v[68:69], v[60:61] op_sel_hi:[1,0]
	v_pk_mul_f32 v[46:47], v[162:163], v[46:47]
	v_pk_mul_f32 v[48:49], v[168:169], v[48:49]
	v_cvt_pk_bf16_f32 v42, v42, v43
	v_cvt_pk_bf16_f32 v43, v44, v45
	v_cvt_pk_bf16_f32 v44, v46, v47
	s_nop 0
	v_cvt_pk_bf16_f32 v45, v48, v49
	global_store_dwordx4 v[62:63], v[42:45], off offset:64
	ds_read_b32 v42, v170 offset:640
	s_waitcnt lgkmcnt(0)
	v_pk_mul_f32 v[40:41], v[40:41], v[42:43] op_sel_hi:[1,0]
	v_pk_mul_f32 v[38:39], v[38:39], v[42:43] op_sel_hi:[1,0]
	v_pk_mul_f32 v[44:45], v[40:41], v[40:41]
	v_pk_mul_f32 v[46:47], v[38:39], v[38:39]
	v_pk_mul_f32 v[36:37], v[36:37], v[42:43] op_sel_hi:[1,0]
	v_pk_mov_b32 v[48:49], v[46:47], v[44:45] op_sel:[1,0]
	v_mov_b32_e32 v47, v45
	v_pk_add_f32 v[44:45], v[48:49], v[46:47]
	v_pk_mul_f32 v[34:35], v[34:35], v[42:43] op_sel_hi:[1,0]
	v_pk_add_f32 v[44:45], v[44:45], v[44:45] op_sel_hi:[0,1]
	v_pk_mul_f32 v[46:47], v[36:37], v[36:37]
	v_pk_mul_f32 v[48:49], v[34:35], v[34:35]
	v_pk_mul_f32 v[30:31], v[30:31], v[42:43] op_sel_hi:[1,0]
	v_pk_mov_b32 v[50:51], v[48:49], v[46:47] op_sel:[1,0]
	v_mov_b32_e32 v49, v47
	v_pk_mul_f32 v[32:33], v[32:33], v[42:43] op_sel_hi:[1,0]
	v_mul_f32_e32 v44, v30, v30
	v_pk_add_f32 v[46:47], v[50:51], v[48:49]
	v_pk_fma_f32 v[48:49], v[30:31], v[30:31], v[44:45] op_sel_hi:[1,1,0]
	v_mul_f32_e32 v44, v32, v32
	v_pk_add_f32 v[46:47], v[46:47], v[46:47] op_sel_hi:[0,1]
	v_pk_fma_f32 v[50:51], v[32:33], v[32:33], v[44:45] op_sel_hi:[1,1,0]
	v_pk_mul_f32 v[52:53], v[28:29], v[42:43] op_sel_hi:[1,0]
	v_pk_mul_f32 v[42:43], v[26:27], v[42:43] op_sel_hi:[1,0]
	v_mul_f32_e32 v44, v52, v52
	v_mul_f32_e32 v48, v42, v42
	v_mul_f32_e32 v50, v43, v43
	v_mul_f32_e32 v46, v53, v53
	v_pk_add_f32 v[26:27], v[48:49], v[50:51]
	v_pk_add_f32 v[28:29], v[44:45], v[46:47]
	s_nop 0
	v_pk_add_f32 v[26:27], v[26:27], v[28:29]
	s_nop 0
	v_add_f32_e32 v26, v26, v27
	v_mov_b32_e32 v27, v26
	s_nop 1
	v_permlane16_swap_b32 v26, v27
	s_nop 1
	v_add_f32_e32 v26, v26, v27
	v_mov_b32_e32 v27, v26
	s_nop 1
	v_permlane32_swap_b32 v26, v27
	s_nop 1
	v_add_f32_e32 v26, v26, v27
	v_fmamk_f32 v26, v26, 0x3c800000, v220
	v_rsq_f32_e32 v27, v26
	v_add_u32_e32 v26, s43, v185
	v_cndmask_b32_e64 v44, 1.0, v27, s[40:41]
	v_ashrrev_i32_e32 v27, 31, v26
	v_lshlrev_b64 v[26:27], s42, v[26:27]
	v_lshl_add_u64 v[46:47], v[26:27], 1, v[122:123]
	v_pk_mul_f32 v[26:27], v[38:39], v[44:45] op_sel_hi:[1,0]
	v_pk_mul_f32 v[28:29], v[40:41], v[44:45] op_sel_hi:[1,0]
	v_pk_mul_f32 v[26:27], v[156:157], v[26:27]
	v_pk_mul_f32 v[28:29], v[158:159], v[28:29]
	v_pk_mul_f32 v[34:35], v[34:35], v[44:45] op_sel_hi:[1,0]
	v_pk_mul_f32 v[36:37], v[36:37], v[44:45] op_sel_hi:[1,0]
	v_pk_mul_f32 v[34:35], v[154:155], v[34:35]
	v_pk_mul_f32 v[36:37], v[160:161], v[36:37]
	v_cvt_pk_bf16_f32 v26, v26, v27
	v_cvt_pk_bf16_f32 v27, v28, v29
	v_cvt_pk_bf16_f32 v28, v34, v35
	s_nop 0
	v_cvt_pk_bf16_f32 v29, v36, v37
	global_store_dwordx4 v[46:47], v[26:29], off
	s_nop 1
	v_pk_mul_f32 v[26:27], v[30:31], v[44:45] op_sel_hi:[1,0]
	v_pk_mul_f32 v[28:29], v[32:33], v[44:45] op_sel_hi:[1,0]
	v_pk_mul_f32 v[26:27], v[164:165], v[26:27]
	v_pk_mul_f32 v[28:29], v[166:167], v[28:29]
	v_pk_mul_f32 v[30:31], v[42:43], v[44:45] op_sel_hi:[1,0]
	v_pk_mul_f32 v[32:33], v[52:53], v[44:45] op_sel_hi:[1,0]
	v_pk_mul_f32 v[30:31], v[162:163], v[30:31]
	v_pk_mul_f32 v[32:33], v[168:169], v[32:33]
	v_cvt_pk_bf16_f32 v26, v26, v27
	v_cvt_pk_bf16_f32 v27, v28, v29
	v_cvt_pk_bf16_f32 v28, v30, v31
	s_nop 0
	v_cvt_pk_bf16_f32 v29, v32, v33
	global_store_dwordx4 v[46:47], v[26:29], off offset:64
	ds_read_b32 v26, v170 offset:704
	s_waitcnt lgkmcnt(0)
	v_pk_mul_f32 v[24:25], v[24:25], v[26:27] op_sel_hi:[1,0]
	v_pk_mul_f32 v[22:23], v[22:23], v[26:27] op_sel_hi:[1,0]
	v_pk_mul_f32 v[28:29], v[24:25], v[24:25]
	v_pk_mul_f32 v[30:31], v[22:23], v[22:23]
	v_pk_mul_f32 v[20:21], v[20:21], v[26:27] op_sel_hi:[1,0]
	v_pk_mov_b32 v[32:33], v[30:31], v[28:29] op_sel:[1,0]
	v_mov_b32_e32 v31, v29
	v_pk_add_f32 v[28:29], v[32:33], v[30:31]
	v_pk_mul_f32 v[18:19], v[18:19], v[26:27] op_sel_hi:[1,0]
	v_pk_add_f32 v[28:29], v[28:29], v[28:29] op_sel_hi:[0,1]
	v_pk_mul_f32 v[30:31], v[20:21], v[20:21]
	v_pk_mul_f32 v[32:33], v[18:19], v[18:19]
	v_pk_mul_f32 v[14:15], v[14:15], v[26:27] op_sel_hi:[1,0]
	v_pk_mov_b32 v[34:35], v[32:33], v[30:31] op_sel:[1,0]
	v_mov_b32_e32 v33, v31
	v_pk_mul_f32 v[16:17], v[16:17], v[26:27] op_sel_hi:[1,0]
	v_mul_f32_e32 v28, v14, v14
	v_pk_add_f32 v[30:31], v[34:35], v[32:33]
	v_pk_fma_f32 v[32:33], v[14:15], v[14:15], v[28:29] op_sel_hi:[1,1,0]
	v_mul_f32_e32 v28, v16, v16
	v_pk_add_f32 v[30:31], v[30:31], v[30:31] op_sel_hi:[0,1]
	v_pk_fma_f32 v[34:35], v[16:17], v[16:17], v[28:29] op_sel_hi:[1,1,0]
	v_pk_mul_f32 v[36:37], v[12:13], v[26:27] op_sel_hi:[1,0]
	v_pk_mul_f32 v[26:27], v[10:11], v[26:27] op_sel_hi:[1,0]
	v_mul_f32_e32 v28, v36, v36
	v_mul_f32_e32 v32, v26, v26
	v_mul_f32_e32 v34, v27, v27
	v_mul_f32_e32 v30, v37, v37
	v_pk_add_f32 v[10:11], v[32:33], v[34:35]
	v_pk_add_f32 v[12:13], v[28:29], v[30:31]
	s_nop 0
	v_pk_add_f32 v[10:11], v[10:11], v[12:13]
	s_nop 0
	v_add_f32_e32 v10, v10, v11
	v_mov_b32_e32 v11, v10
	s_nop 1
	v_permlane16_swap_b32 v10, v11
	s_nop 1
	v_add_f32_e32 v10, v10, v11
	v_mov_b32_e32 v11, v10
	s_nop 1
	v_permlane32_swap_b32 v10, v11
	s_nop 1
	v_add_f32_e32 v10, v10, v11
	v_fmamk_f32 v10, v10, 0x3c800000, v220
	v_rsq_f32_e32 v11, v10
	v_add_u32_e32 v10, s43, v186
	v_cndmask_b32_e64 v28, 1.0, v11, s[40:41]
	v_ashrrev_i32_e32 v11, 31, v10
	v_lshlrev_b64 v[10:11], s42, v[10:11]
	v_lshl_add_u64 v[30:31], v[10:11], 1, v[122:123]
	v_pk_mul_f32 v[10:11], v[22:23], v[28:29] op_sel_hi:[1,0]
	v_pk_mul_f32 v[12:13], v[24:25], v[28:29] op_sel_hi:[1,0]
	v_pk_mul_f32 v[10:11], v[156:157], v[10:11]
	v_pk_mul_f32 v[12:13], v[158:159], v[12:13]
	v_pk_mul_f32 v[18:19], v[18:19], v[28:29] op_sel_hi:[1,0]
	v_pk_mul_f32 v[20:21], v[20:21], v[28:29] op_sel_hi:[1,0]
	v_pk_mul_f32 v[18:19], v[154:155], v[18:19]
	v_pk_mul_f32 v[20:21], v[160:161], v[20:21]
	v_cvt_pk_bf16_f32 v10, v10, v11
	v_cvt_pk_bf16_f32 v11, v12, v13
	v_cvt_pk_bf16_f32 v12, v18, v19
	s_nop 0
	v_cvt_pk_bf16_f32 v13, v20, v21
	global_store_dwordx4 v[30:31], v[10:13], off
	s_nop 1
	v_pk_mul_f32 v[10:11], v[14:15], v[28:29] op_sel_hi:[1,0]
	v_pk_mul_f32 v[12:13], v[16:17], v[28:29] op_sel_hi:[1,0]
	v_pk_mul_f32 v[10:11], v[164:165], v[10:11]
	v_pk_mul_f32 v[12:13], v[166:167], v[12:13]
	v_pk_mul_f32 v[14:15], v[26:27], v[28:29] op_sel_hi:[1,0]
	v_pk_mul_f32 v[16:17], v[36:37], v[28:29] op_sel_hi:[1,0]
	v_pk_mul_f32 v[14:15], v[162:163], v[14:15]
	v_pk_mul_f32 v[16:17], v[168:169], v[16:17]
	v_cvt_pk_bf16_f32 v10, v10, v11
	v_cvt_pk_bf16_f32 v11, v12, v13
	v_cvt_pk_bf16_f32 v12, v14, v15
	s_nop 0
	v_cvt_pk_bf16_f32 v13, v16, v17
	global_store_dwordx4 v[30:31], v[10:13], off offset:64
	s_cbranch_vccnz .LBB0_660
	s_waitcnt vmcnt(0)
	v_add_f32_e32 v10, v6, v7
	v_add_f32_e32 v11, v8, v9
	v_add_f32_e32 v10, v10, v11
	v_add_f32_e32 v11, v2, v3
	v_add_f32_e32 v12, v4, v5
	v_add_f32_e32 v11, v11, v12
	v_add_f32_e32 v10, v11, v10
	s_nop 1
	v_mov_b32_dpp v11, v10 quad_perm:[1,0,3,2] row_mask:0xf bank_mask:0xf
	s_nop 1
	s_and_saveexec_b64 s[38:39], s[36:37]
	s_cbranch_execz .LBB0_680
	s_waitcnt lgkmcnt(0)
	v_add_f32_e32 v10, v10, v11
	v_fmamk_f32 v10, v10, 0x3a800000, v220
	v_rsq_f32_e32 v10, v10
	s_lshl_b32 s40, s80, 10
	s_and_b32 s40, s40, 0x400
	v_add_u32_e32 v11, s40, v177
	ds_write_b32 v11, v10
